# attention main loops: next-tile LDS-DMA pieces issued between the QK MFMAs instead of in a branchy block before them (old block kept for wave-tiles that skip the body)
# speedup vs baseline: 1.0167x; 1.0096x over previous
; __device__ __forceinline__ void attn_unit(LAS unsigned char* lds, int b, int h, int qb, const bf16_t* Q, const bf16_t* KF, const bf16_t* VT,
;                                           const float* gout, bf16_t* MIXED, int wave, int lane) {
;     ...
;     for (int kt = 0; kt < nkt; ++kt) {
;         if (kt + 1 < nkt) ATT_ISSUE(kt + 1, (kt + 1) & 1);
;         const int key0 = kt * 64;
;         if (key0 <= q0w + 31) {
.LBB0_440:
	s_add_i32 s88, s85, 1
	s_bitcmp1_b32 s88, 0
	s_cselect_b32 s56, 0xac00, 0
	s_and_b64 vcc, exec, s[4:5]
	s_add_i32 s81, s56, 0
	s_cmp_gt_i32 s80, s70
	s_cbranch_scc0 .LBB0_453
	s_cbranch_vccz .LBB0_447
	s_and_b64 vcc, exec, s[6:7]
	s_cbranch_vccz .LBB0_448

; #define LAS __attribute__((address_space(3)))
; __device__ __forceinline__ void attn_unit(LAS unsigned char* lds, int b, int h, int qb, const bf16_t* Q, const bf16_t* KF, const bf16_t* VT,
;                                           const float* gout, bf16_t* MIXED, int wave, int lane) {
;     ...
;             const LAS unsigned char* kb_ = lds + (kt & 1) * ABUF;
;             const LAS unsigned char* vb_ = kb_ + KT_BYTES;
;             f32x16 sacc[2];
;             __builtin_amdgcn_s_setprio(1);
; #pragma unroll
;             for (int kb = 0; kb < 2; ++kb) {
; #pragma unroll
;                 for (int i = 0; i < 16; ++i) sacc[kb][i] = 0.f;
; #pragma unroll
;                 for (int ks = 0; ks < 12; ++ks) { const bf16x8 kf = *(const LAS bf16x8*)(kb_ + (kb * 32 + l31) * KT_STRIDE + ks * 32 + hi * 16);
;                     sacc[kb] = __builtin_amdgcn_mfma_f32_32x32x16_bf16(kf, qf[ks], sacc[kb], 0, 0, 0); }
;                 __builtin_amdgcn_sched_barrier(0);
;             }
.LBB0_453:
	s_bitcmp1_b32 s85, 0
	s_cselect_b32 s56, 0xac00, 0
	s_setprio 1
	v_add_u32_e32 v107, s56, v106
	v_add_u32_e32 v114, v107, v113
	ds_read_b128 v[224:227], v114
	ds_read_b128 v[228:231], v114 offset:32
	ds_read_b128 v[80:83], v114 offset:64
	s_waitcnt lgkmcnt(2)
	v_mfma_f32_32x32x16_bf16 v[64:79], v[224:227], v[128:131], 0
	ds_read_b128 v[224:227], v114 offset:96
	s_waitcnt lgkmcnt(2)
	v_mfma_f32_32x32x16_bf16 v[64:79], v[228:231], v[200:203], v[64:79]
	s_add_i32 m0, s81, s0
	s_and_b64 vcc, s[72:73], exec
	s_cselect_b64 s[56:57], s[62:63], s[52:53]
	v_lshl_add_u64 v[232:233], v[96:97], 1, s[56:57]
	global_load_lds_dwordx4 v[232:233], off
	ds_read_b128 v[228:231], v114 offset:128
	s_waitcnt lgkmcnt(2)
	v_mfma_f32_32x32x16_bf16 v[64:79], v[80:83], v[196:199], v[64:79]
	ds_read_b128 v[80:83], v114 offset:160
	s_waitcnt lgkmcnt(2)
	v_mfma_f32_32x32x16_bf16 v[64:79], v[224:227], v[192:195], v[64:79]
	ds_read_b128 v[224:227], v114 offset:192
	s_waitcnt lgkmcnt(2)
	v_mfma_f32_32x32x16_bf16 v[64:79], v[228:231], v[188:191], v[64:79]
	ds_read_b128 v[228:231], v114 offset:224
	s_waitcnt lgkmcnt(2)
	v_mfma_f32_32x32x16_bf16 v[64:79], v[80:83], v[184:187], v[64:79]
	s_add_i32 m0, s81, s44
	s_and_b64 vcc, s[82:83], exec
	s_cselect_b64 s[56:57], s[62:63], s[52:53]
	v_lshl_add_u64 v[232:233], v[98:99], 1, s[56:57]
	global_load_lds_dwordx4 v[232:233], off
	ds_read_b128 v[80:83], v114 offset:256
	s_waitcnt lgkmcnt(2)
	v_mfma_f32_32x32x16_bf16 v[64:79], v[224:227], v[180:183], v[64:79]
	ds_read_b128 v[224:227], v114 offset:288
	s_waitcnt lgkmcnt(2)
	v_mfma_f32_32x32x16_bf16 v[64:79], v[228:231], v[176:179], v[64:79]
	ds_read_b128 v[228:231], v114 offset:320
	s_waitcnt lgkmcnt(2)
	v_mfma_f32_32x32x16_bf16 v[64:79], v[80:83], v[172:175], v[64:79]
	ds_read_b128 v[80:83], v114 offset:352
	s_waitcnt lgkmcnt(2)
	v_mfma_f32_32x32x16_bf16 v[64:79], v[224:227], v[168:171], v[64:79]
	s_add_i32 m0, s81, s45
	s_and_b64 vcc, s[92:93], exec
	s_cselect_b64 s[56:57], s[62:63], s[52:53]
	v_lshl_add_u64 v[232:233], v[100:101], 1, s[56:57]
	global_load_lds_dwordx4 v[232:233], off
	ds_read_b128 v[224:227], v114 offset:12800
	s_waitcnt lgkmcnt(2)
	v_mfma_f32_32x32x16_bf16 v[64:79], v[228:231], v[164:167], v[64:79]
	ds_read_b128 v[228:231], v114 offset:12832
	s_waitcnt lgkmcnt(2)
	v_mfma_f32_32x32x16_bf16 v[64:79], v[80:83], v[160:163], v[64:79]
	ds_read_b128 v[108:111], v114 offset:12864
	s_waitcnt lgkmcnt(2)
	v_mfma_f32_32x32x16_bf16 v[80:95], v[224:227], v[128:131], 0
	ds_read_b128 v[224:227], v114 offset:12896
	s_waitcnt lgkmcnt(2)
	v_mfma_f32_32x32x16_bf16 v[80:95], v[228:231], v[200:203], v[80:95]
	s_add_i32 m0, s81, s1
	s_and_b64 vcc, s[66:67], exec
	s_cselect_b64 s[56:57], s[62:63], s[52:53]
	v_lshl_add_u64 v[232:233], v[102:103], 1, s[56:57]
	global_load_lds_dwordx4 v[232:233], off
	ds_read_b128 v[228:231], v114 offset:12928
	s_waitcnt lgkmcnt(2)
	v_mfma_f32_32x32x16_bf16 v[80:95], v[108:111], v[196:199], v[80:95]
	ds_read_b128 v[108:111], v114 offset:12960
	s_waitcnt lgkmcnt(2)
	v_mfma_f32_32x32x16_bf16 v[80:95], v[224:227], v[192:195], v[80:95]
	ds_read_b128 v[224:227], v114 offset:12992
	s_waitcnt lgkmcnt(2)
	v_mfma_f32_32x32x16_bf16 v[80:95], v[228:231], v[188:191], v[80:95]
	ds_read_b128 v[228:231], v114 offset:13024
	s_waitcnt lgkmcnt(2)
	v_mfma_f32_32x32x16_bf16 v[80:95], v[108:111], v[184:187], v[80:95]
	s_add_i32 m0, s81, s64
	s_and_b64 vcc, s[90:91], exec
	s_cselect_b64 s[56:57], s[62:63], s[52:53]
	v_lshl_add_u64 v[232:233], v[104:105], 1, s[56:57]
	global_load_lds_dwordx4 v[232:233], off
	ds_read_b128 v[108:111], v114 offset:13056
	s_waitcnt lgkmcnt(2)
	v_mfma_f32_32x32x16_bf16 v[80:95], v[224:227], v[180:183], v[80:95]
	ds_read_b128 v[224:227], v114 offset:13088
	s_waitcnt lgkmcnt(2)
	v_mfma_f32_32x32x16_bf16 v[80:95], v[228:231], v[176:179], v[80:95]
	ds_read_b128 v[228:231], v114 offset:13120
	s_waitcnt lgkmcnt(2)
	v_mfma_f32_32x32x16_bf16 v[80:95], v[108:111], v[172:175], v[80:95]
	ds_read_b128 v[108:111], v114 offset:13152
	s_waitcnt lgkmcnt(2)
	v_mfma_f32_32x32x16_bf16 v[80:95], v[224:227], v[168:171], v[80:95]
	s_and_b64 vcc, exec, s[14:15]
	s_cbranch_vccnz .Ldma5_skip_a
	s_add_i32 m0, s81, s65
	s_and_b64 vcc, s[78:79], exec
	s_cselect_b64 s[56:57], s[62:63], s[52:53]
	v_lshl_add_u64 v[232:233], v[206:207], 1, s[56:57]
	global_load_lds_dwordx4 v[232:233], off
; #define LAS __attribute__((address_space(3)))
; __device__ __forceinline__ int crow(int r, int hi) { return (r & 3) + 8 * (r >> 2) + 4 * hi; }
; __device__ __forceinline__ void attn_unit(LAS unsigned char* lds, int b, int h, int qb, const bf16_t* Q, const bf16_t* KF, const bf16_t* VT,
;                                           const float* gout, bf16_t* MIXED, int wave, int lane) {
;     ...
;                 for (int ks = 0; ks < 12; ++ks) { const bf16x8 kf = *(const LAS bf16x8*)(kb_ + (kb * 32 + l31) * KT_STRIDE + ks * 32 + hi * 16);
;                     sacc[kb] = __builtin_amdgcn_mfma_f32_32x32x16_bf16(kf, qf[ks], sacc[kb], 0, 0, 0); }
;                 __builtin_amdgcn_sched_barrier(0);
;             }
;             __builtin_amdgcn_s_setprio(0);
;             if (key0 + 63 > q0w) {
; #pragma unroll
;                 for (int kb = 0; kb < 2; ++kb)
; #pragma unroll
;                     for (int i = 0; i < 16; ++i) { const int key = key0 + kb * 32 + crow(i, hi); if (key > qpos) sacc[kb][i] = -INFINITY; }
;             }
.Ldma5_skip_a:
	s_waitcnt lgkmcnt(1)
	v_mfma_f32_32x32x16_bf16 v[80:95], v[228:231], v[164:167], v[80:95]
	s_waitcnt lgkmcnt(0)
	v_mfma_f32_32x32x16_bf16 v[80:95], v[108:111], v[160:163], v[80:95]
	s_setprio 0
	s_add_i32 s56, s80, 63
	s_cmp_le_i32 s56, s61
	s_cbranch_scc1 .LBB0_455
	v_add_u32_e32 v108, s80, v210
	v_cmp_gt_i32_e32 vcc, v108, v212
	s_nop 1
	v_cndmask_b32_e32 v109, v64, v218, vcc
	v_cmp_lt_i32_e32 vcc, v108, v212
	s_nop 1
	v_cndmask_b32_e32 v64, v109, v64, vcc
	v_add_u32_e32 v109, 2, v108
	v_cndmask_b32_e32 v65, v218, v65, vcc
	v_cmp_le_i32_e32 vcc, v109, v212
	v_add_u32_e32 v109, 3, v108
	s_nop 0
	v_cndmask_b32_e32 v66, v218, v66, vcc
	v_cmp_le_i32_e32 vcc, v109, v212
	v_add_u32_e32 v109, 8, v108
	s_nop 0
	v_cndmask_b32_e32 v67, v218, v67, vcc
	v_cmp_le_i32_e32 vcc, v109, v212
	v_add_u32_e32 v109, 9, v108
	s_nop 0
	v_cndmask_b32_e32 v68, v218, v68, vcc
	v_cmp_le_i32_e32 vcc, v109, v212
	v_add_u32_e32 v109, 10, v108
	s_nop 0
	v_cndmask_b32_e32 v69, v218, v69, vcc
	v_cmp_le_i32_e32 vcc, v109, v212
	v_add_u32_e32 v109, 11, v108
	s_nop 0
	v_cndmask_b32_e32 v70, v218, v70, vcc
	v_cmp_le_i32_e32 vcc, v109, v212
	v_add_u32_e32 v109, 16, v108
	s_nop 0
	v_cndmask_b32_e32 v71, v218, v71, vcc
	v_cmp_le_i32_e32 vcc, v109, v212
	v_add_u32_e32 v109, 17, v108
	s_nop 0
	v_cndmask_b32_e32 v72, v218, v72, vcc
	v_cmp_le_i32_e32 vcc, v109, v212
	v_add_u32_e32 v109, 18, v108
	s_nop 0
	v_cndmask_b32_e32 v73, v218, v73, vcc
	v_cmp_le_i32_e32 vcc, v109, v212
	v_add_u32_e32 v109, 19, v108
	s_nop 0
	v_cndmask_b32_e32 v74, v218, v74, vcc
	v_cmp_le_i32_e32 vcc, v109, v212
	v_add_u32_e32 v109, 24, v108
	s_nop 0
	v_cndmask_b32_e32 v75, v218, v75, vcc
	v_cmp_le_i32_e32 vcc, v109, v212
	v_add_u32_e32 v109, 25, v108
	s_nop 0
	v_cndmask_b32_e32 v76, v218, v76, vcc
	v_cmp_le_i32_e32 vcc, v109, v212
	v_add_u32_e32 v109, 26, v108
	s_nop 0
	v_cndmask_b32_e32 v77, v218, v77, vcc
	v_cmp_le_i32_e32 vcc, v109, v212
	v_add_u32_e32 v109, 27, v108
	s_nop 0
	v_cndmask_b32_e32 v78, v218, v78, vcc
	v_cmp_le_i32_e32 vcc, v109, v212
	v_add_u32_e32 v109, 32, v108
	s_nop 0
	v_cndmask_b32_e32 v79, v218, v79, vcc
	v_cmp_le_i32_e32 vcc, v109, v212
	s_nop 1
	v_cndmask_b32_e32 v80, v218, v80, vcc
	v_cmp_lt_i32_e32 vcc, v109, v212
	v_add_u32_e32 v109, 34, v108
	s_nop 0
	v_cndmask_b32_e32 v81, v218, v81, vcc
	v_cmp_le_i32_e32 vcc, v109, v212
	v_add_u32_e32 v109, 35, v108
	s_nop 0
	v_cndmask_b32_e32 v82, v218, v82, vcc
	v_cmp_le_i32_e32 vcc, v109, v212
	v_add_u32_e32 v109, 40, v108
	s_nop 0
	v_cndmask_b32_e32 v83, v218, v83, vcc
	v_cmp_le_i32_e32 vcc, v109, v212
	v_add_u32_e32 v109, 41, v108
	s_nop 0
	v_cndmask_b32_e32 v84, v218, v84, vcc
	v_cmp_le_i32_e32 vcc, v109, v212
	v_add_u32_e32 v109, 42, v108
	s_nop 0
	v_cndmask_b32_e32 v85, v218, v85, vcc
	v_cmp_le_i32_e32 vcc, v109, v212
	v_add_u32_e32 v109, 43, v108
	s_nop 0
	v_cndmask_b32_e32 v86, v218, v86, vcc
	v_cmp_le_i32_e32 vcc, v109, v212
	v_add_u32_e32 v109, 48, v108
	s_nop 0
	v_cndmask_b32_e32 v87, v218, v87, vcc
	v_cmp_le_i32_e32 vcc, v109, v212
	v_add_u32_e32 v109, 49, v108
	s_nop 0
	v_cndmask_b32_e32 v88, v218, v88, vcc
	v_cmp_le_i32_e32 vcc, v109, v212
	v_add_u32_e32 v109, 50, v108
	s_nop 0
	v_cndmask_b32_e32 v89, v218, v89, vcc
	v_cmp_le_i32_e32 vcc, v109, v212
	v_add_u32_e32 v109, 51, v108
	s_nop 0
	v_cndmask_b32_e32 v90, v218, v90, vcc
	v_cmp_le_i32_e32 vcc, v109, v212
	v_add_u32_e32 v109, 56, v108
	s_nop 0
	v_cndmask_b32_e32 v91, v218, v91, vcc
	v_cmp_le_i32_e32 vcc, v109, v212
	v_add_u32_e32 v109, 57, v108
	s_nop 0
	v_cndmask_b32_e32 v92, v218, v92, vcc
	v_cmp_le_i32_e32 vcc, v109, v212
	v_add_u32_e32 v109, 58, v108
	v_add_u32_e32 v108, 59, v108
	v_cndmask_b32_e32 v93, v218, v93, vcc
	v_cmp_le_i32_e32 vcc, v109, v212
	s_nop 1
	v_cndmask_b32_e32 v94, v218, v94, vcc
	v_cmp_le_i32_e32 vcc, v108, v212
	s_nop 1
	v_cndmask_b32_e32 v95, v218, v95, vcc

; __device__ __forceinline__ void attn_unit(LAS unsigned char* lds, int b, int h, int qb, const bf16_t* Q, const bf16_t* KF, const bf16_t* VT,
;                                           const float* gout, bf16_t* MIXED, int wave, int lane) {
;     ...
;     for (int kt = 0; kt < nkt; ++kt) {
;         if (kt + 1 < nkt) ATT_ISSUE(kt + 1, (kt + 1) & 1);
;         const int key0 = kt * 64;
;         if (key0 <= q0w + 31) {
.LBB0_493:
	s_add_i32 s24, s25, 1
	s_bitcmp1_b32 s24, 0
	s_cselect_b32 s23, 0xac00, 0
	s_and_b64 vcc, exec, s[4:5]
	s_add_i32 s23, s23, 0
	s_cmp_gt_i32 s22, s21
	s_cbranch_scc0 .LBB0_506
	s_cbranch_vccz .LBB0_500
	s_and_b64 vcc, exec, s[6:7]
	s_cbranch_vccz .LBB0_501

; #define LAS __attribute__((address_space(3)))
; __device__ __forceinline__ void attn_unit(LAS unsigned char* lds, int b, int h, int qb, const bf16_t* Q, const bf16_t* KF, const bf16_t* VT,
;                                           const float* gout, bf16_t* MIXED, int wave, int lane) {
;     ...
;             const LAS unsigned char* kb_ = lds + (kt & 1) * ABUF;
;             const LAS unsigned char* vb_ = kb_ + KT_BYTES;
;             f32x16 sacc[2];
;             __builtin_amdgcn_s_setprio(1);
; #pragma unroll
;             for (int kb = 0; kb < 2; ++kb) {
; #pragma unroll
;                 for (int i = 0; i < 16; ++i) sacc[kb][i] = 0.f;
; #pragma unroll
;                 for (int ks = 0; ks < 12; ++ks) { const bf16x8 kf = *(const LAS bf16x8*)(kb_ + (kb * 32 + l31) * KT_STRIDE + ks * 32 + hi * 16);
;                     sacc[kb] = __builtin_amdgcn_mfma_f32_32x32x16_bf16(kf, qf[ks], sacc[kb], 0, 0, 0); }
;                 __builtin_amdgcn_sched_barrier(0);
;             }
.LBB0_506:
	s_bitcmp1_b32 s25, 0
	s_cselect_b32 s25, 0xac00, 0
	s_setprio 1
	v_add_u32_e32 v109, s25, v108
	v_add_u32_e32 v114, v109, v107
	ds_read_b128 v[224:227], v114
	ds_read_b128 v[228:231], v114 offset:32
	ds_read_b128 v[80:83], v114 offset:64
	s_waitcnt lgkmcnt(2)
	v_mfma_f32_32x32x16_bf16 v[64:79], v[224:227], v[128:131], 0
	ds_read_b128 v[224:227], v114 offset:96
	s_waitcnt lgkmcnt(2)
	v_mfma_f32_32x32x16_bf16 v[64:79], v[228:231], v[200:203], v[64:79]
	s_add_i32 m0, s23, s0
	s_and_b64 s[26:27], s[72:73], exec
	s_cselect_b64 s[26:27], s[18:19], s[16:17]
	v_lshl_add_u64 v[232:233], v[96:97], 1, s[26:27]
	global_load_lds_dwordx4 v[232:233], off
	ds_read_b128 v[228:231], v114 offset:128
	s_waitcnt lgkmcnt(2)
	v_mfma_f32_32x32x16_bf16 v[64:79], v[80:83], v[196:199], v[64:79]
	ds_read_b128 v[80:83], v114 offset:160
	s_waitcnt lgkmcnt(2)
	v_mfma_f32_32x32x16_bf16 v[64:79], v[224:227], v[192:195], v[64:79]
	ds_read_b128 v[224:227], v114 offset:192
	s_waitcnt lgkmcnt(2)
	v_mfma_f32_32x32x16_bf16 v[64:79], v[228:231], v[188:191], v[64:79]
	ds_read_b128 v[228:231], v114 offset:224
	s_waitcnt lgkmcnt(2)
	v_mfma_f32_32x32x16_bf16 v[64:79], v[80:83], v[184:187], v[64:79]
	s_add_i32 m0, s23, s44
	s_and_b64 s[26:27], s[82:83], exec
	s_cselect_b64 s[26:27], s[18:19], s[16:17]
	v_lshl_add_u64 v[232:233], v[98:99], 1, s[26:27]
	global_load_lds_dwordx4 v[232:233], off
	ds_read_b128 v[80:83], v114 offset:256
	s_waitcnt lgkmcnt(2)
	v_mfma_f32_32x32x16_bf16 v[64:79], v[224:227], v[180:183], v[64:79]
	ds_read_b128 v[224:227], v114 offset:288
	s_waitcnt lgkmcnt(2)
	v_mfma_f32_32x32x16_bf16 v[64:79], v[228:231], v[176:179], v[64:79]
	ds_read_b128 v[228:231], v114 offset:320
	s_waitcnt lgkmcnt(2)
	v_mfma_f32_32x32x16_bf16 v[64:79], v[80:83], v[172:175], v[64:79]
	ds_read_b128 v[80:83], v114 offset:352
	s_waitcnt lgkmcnt(2)
	v_mfma_f32_32x32x16_bf16 v[64:79], v[224:227], v[168:171], v[64:79]
	s_add_i32 m0, s23, s45
	s_and_b64 s[26:27], s[92:93], exec
	s_cselect_b64 s[26:27], s[18:19], s[16:17]
	v_lshl_add_u64 v[232:233], v[100:101], 1, s[26:27]
	global_load_lds_dwordx4 v[232:233], off
	ds_read_b128 v[224:227], v114 offset:12800
	s_waitcnt lgkmcnt(2)
	v_mfma_f32_32x32x16_bf16 v[64:79], v[228:231], v[164:167], v[64:79]
	ds_read_b128 v[228:231], v114 offset:12832
	s_waitcnt lgkmcnt(2)
	v_mfma_f32_32x32x16_bf16 v[64:79], v[80:83], v[160:163], v[64:79]
	ds_read_b128 v[110:113], v114 offset:12864
	s_waitcnt lgkmcnt(2)
	v_mfma_f32_32x32x16_bf16 v[80:95], v[224:227], v[128:131], 0
	ds_read_b128 v[224:227], v114 offset:12896
	s_waitcnt lgkmcnt(2)
	v_mfma_f32_32x32x16_bf16 v[80:95], v[228:231], v[200:203], v[80:95]
	s_add_i32 m0, s23, s1
	s_and_b64 s[26:27], s[66:67], exec
	s_cselect_b64 s[26:27], s[18:19], s[16:17]
	v_lshl_add_u64 v[232:233], v[102:103], 1, s[26:27]
	global_load_lds_dwordx4 v[232:233], off
	ds_read_b128 v[228:231], v114 offset:12928
	s_waitcnt lgkmcnt(2)
	v_mfma_f32_32x32x16_bf16 v[80:95], v[110:113], v[196:199], v[80:95]
	ds_read_b128 v[110:113], v114 offset:12960
	s_waitcnt lgkmcnt(2)
	v_mfma_f32_32x32x16_bf16 v[80:95], v[224:227], v[192:195], v[80:95]
	ds_read_b128 v[224:227], v114 offset:12992
	s_waitcnt lgkmcnt(2)
	v_mfma_f32_32x32x16_bf16 v[80:95], v[228:231], v[188:191], v[80:95]
	ds_read_b128 v[228:231], v114 offset:13024
	s_waitcnt lgkmcnt(2)
	v_mfma_f32_32x32x16_bf16 v[80:95], v[110:113], v[184:187], v[80:95]
	s_add_i32 m0, s23, s64
	s_and_b64 s[26:27], s[90:91], exec
	s_cselect_b64 s[26:27], s[18:19], s[16:17]
	v_lshl_add_u64 v[232:233], v[104:105], 1, s[26:27]
	global_load_lds_dwordx4 v[232:233], off
	ds_read_b128 v[110:113], v114 offset:13056
	s_waitcnt lgkmcnt(2)
	v_mfma_f32_32x32x16_bf16 v[80:95], v[224:227], v[180:183], v[80:95]
	ds_read_b128 v[224:227], v114 offset:13088
	s_waitcnt lgkmcnt(2)
	v_mfma_f32_32x32x16_bf16 v[80:95], v[228:231], v[176:179], v[80:95]
	ds_read_b128 v[228:231], v114 offset:13120
	s_waitcnt lgkmcnt(2)
	v_mfma_f32_32x32x16_bf16 v[80:95], v[110:113], v[172:175], v[80:95]
	ds_read_b128 v[110:113], v114 offset:13152
	s_waitcnt lgkmcnt(2)
	v_mfma_f32_32x32x16_bf16 v[80:95], v[224:227], v[168:171], v[80:95]
	s_and_b64 vcc, exec, s[14:15]
	s_cbranch_vccnz .Ldma5_skip_b
	s_add_i32 m0, s23, s65
	s_and_b64 s[26:27], s[78:79], exec
	s_cselect_b64 s[26:27], s[18:19], s[16:17]
	v_lshl_add_u64 v[232:233], v[206:207], 1, s[26:27]
	global_load_lds_dwordx4 v[232:233], off
; #define LAS __attribute__((address_space(3)))
; __device__ __forceinline__ int crow(int r, int hi) { return (r & 3) + 8 * (r >> 2) + 4 * hi; }
; __device__ __forceinline__ void attn_unit(LAS unsigned char* lds, int b, int h, int qb, const bf16_t* Q, const bf16_t* KF, const bf16_t* VT,
;                                           const float* gout, bf16_t* MIXED, int wave, int lane) {
;     ...
;                 for (int ks = 0; ks < 12; ++ks) { const bf16x8 kf = *(const LAS bf16x8*)(kb_ + (kb * 32 + l31) * KT_STRIDE + ks * 32 + hi * 16);
;                     sacc[kb] = __builtin_amdgcn_mfma_f32_32x32x16_bf16(kf, qf[ks], sacc[kb], 0, 0, 0); }
;                 __builtin_amdgcn_sched_barrier(0);
;             }
;             __builtin_amdgcn_s_setprio(0);
;             if (key0 + 63 > q0w) {
; #pragma unroll
;                 for (int kb = 0; kb < 2; ++kb)
; #pragma unroll
;                     for (int i = 0; i < 16; ++i) { const int key = key0 + kb * 32 + crow(i, hi); if (key > qpos) sacc[kb][i] = -INFINITY; }
;             }
.Ldma5_skip_b:
	s_waitcnt lgkmcnt(1)
	v_mfma_f32_32x32x16_bf16 v[80:95], v[228:231], v[164:167], v[80:95]
	s_waitcnt lgkmcnt(0)
	v_mfma_f32_32x32x16_bf16 v[80:95], v[110:113], v[160:163], v[80:95]
	s_setprio 0
	s_add_i32 s25, s22, 63
	s_cmp_le_i32 s25, s63
	s_cbranch_scc1 .LBB0_508
	v_add_u32_e32 v110, s22, v210
	v_cmp_gt_i32_e32 vcc, v110, v212
	s_nop 1
	v_cndmask_b32_e32 v111, v64, v218, vcc
	v_cmp_lt_i32_e32 vcc, v110, v212
	s_nop 1
	v_cndmask_b32_e32 v64, v111, v64, vcc
	v_add_u32_e32 v111, 2, v110
	v_cndmask_b32_e32 v65, v218, v65, vcc
	v_cmp_le_i32_e32 vcc, v111, v212
	v_add_u32_e32 v111, 3, v110
	s_nop 0
	v_cndmask_b32_e32 v66, v218, v66, vcc
	v_cmp_le_i32_e32 vcc, v111, v212
	v_add_u32_e32 v111, 8, v110
	s_nop 0
	v_cndmask_b32_e32 v67, v218, v67, vcc
	v_cmp_le_i32_e32 vcc, v111, v212
	v_add_u32_e32 v111, 9, v110
	s_nop 0
	v_cndmask_b32_e32 v68, v218, v68, vcc
	v_cmp_le_i32_e32 vcc, v111, v212
	v_add_u32_e32 v111, 10, v110
	s_nop 0
	v_cndmask_b32_e32 v69, v218, v69, vcc
	v_cmp_le_i32_e32 vcc, v111, v212
	v_add_u32_e32 v111, 11, v110
	s_nop 0
	v_cndmask_b32_e32 v70, v218, v70, vcc
	v_cmp_le_i32_e32 vcc, v111, v212
	v_add_u32_e32 v111, 16, v110
	s_nop 0
	v_cndmask_b32_e32 v71, v218, v71, vcc
	v_cmp_le_i32_e32 vcc, v111, v212
	v_add_u32_e32 v111, 17, v110
	s_nop 0
	v_cndmask_b32_e32 v72, v218, v72, vcc
	v_cmp_le_i32_e32 vcc, v111, v212
	v_add_u32_e32 v111, 18, v110
	s_nop 0
	v_cndmask_b32_e32 v73, v218, v73, vcc
	v_cmp_le_i32_e32 vcc, v111, v212
	v_add_u32_e32 v111, 19, v110
	s_nop 0
	v_cndmask_b32_e32 v74, v218, v74, vcc
	v_cmp_le_i32_e32 vcc, v111, v212
	v_add_u32_e32 v111, 24, v110
	s_nop 0
	v_cndmask_b32_e32 v75, v218, v75, vcc
	v_cmp_le_i32_e32 vcc, v111, v212
	v_add_u32_e32 v111, 25, v110
	s_nop 0
	v_cndmask_b32_e32 v76, v218, v76, vcc
	v_cmp_le_i32_e32 vcc, v111, v212
	v_add_u32_e32 v111, 26, v110
	s_nop 0
	v_cndmask_b32_e32 v77, v218, v77, vcc
	v_cmp_le_i32_e32 vcc, v111, v212
	v_add_u32_e32 v111, 27, v110
	s_nop 0
	v_cndmask_b32_e32 v78, v218, v78, vcc
	v_cmp_le_i32_e32 vcc, v111, v212
	v_add_u32_e32 v111, 32, v110
	s_nop 0
	v_cndmask_b32_e32 v79, v218, v79, vcc
	v_cmp_le_i32_e32 vcc, v111, v212
	s_nop 1
	v_cndmask_b32_e32 v80, v218, v80, vcc
	v_cmp_lt_i32_e32 vcc, v111, v212
	v_add_u32_e32 v111, 34, v110
	s_nop 0
	v_cndmask_b32_e32 v81, v218, v81, vcc
	v_cmp_le_i32_e32 vcc, v111, v212
	v_add_u32_e32 v111, 35, v110
	s_nop 0
	v_cndmask_b32_e32 v82, v218, v82, vcc
	v_cmp_le_i32_e32 vcc, v111, v212
	v_add_u32_e32 v111, 40, v110
	s_nop 0
	v_cndmask_b32_e32 v83, v218, v83, vcc
	v_cmp_le_i32_e32 vcc, v111, v212
	v_add_u32_e32 v111, 41, v110
	s_nop 0
	v_cndmask_b32_e32 v84, v218, v84, vcc
	v_cmp_le_i32_e32 vcc, v111, v212
	v_add_u32_e32 v111, 42, v110
	s_nop 0
	v_cndmask_b32_e32 v85, v218, v85, vcc
	v_cmp_le_i32_e32 vcc, v111, v212
	v_add_u32_e32 v111, 43, v110
	s_nop 0
	v_cndmask_b32_e32 v86, v218, v86, vcc
	v_cmp_le_i32_e32 vcc, v111, v212
	v_add_u32_e32 v111, 48, v110
	s_nop 0
	v_cndmask_b32_e32 v87, v218, v87, vcc
	v_cmp_le_i32_e32 vcc, v111, v212
	v_add_u32_e32 v111, 49, v110
	s_nop 0
	v_cndmask_b32_e32 v88, v218, v88, vcc
	v_cmp_le_i32_e32 vcc, v111, v212
	v_add_u32_e32 v111, 50, v110
	s_nop 0
	v_cndmask_b32_e32 v89, v218, v89, vcc
	v_cmp_le_i32_e32 vcc, v111, v212
	v_add_u32_e32 v111, 51, v110
	s_nop 0
	v_cndmask_b32_e32 v90, v218, v90, vcc
	v_cmp_le_i32_e32 vcc, v111, v212
	v_add_u32_e32 v111, 56, v110
	s_nop 0
	v_cndmask_b32_e32 v91, v218, v91, vcc
	v_cmp_le_i32_e32 vcc, v111, v212
	v_add_u32_e32 v111, 57, v110
	s_nop 0
	v_cndmask_b32_e32 v92, v218, v92, vcc
	v_cmp_le_i32_e32 vcc, v111, v212
	v_add_u32_e32 v111, 58, v110
	v_add_u32_e32 v110, 59, v110
	v_cndmask_b32_e32 v93, v218, v93, vcc
	v_cmp_le_i32_e32 vcc, v111, v212
	s_nop 1
	v_cndmask_b32_e32 v94, v218, v94, vcc
	v_cmp_le_i32_e32 vcc, v110, v212
	s_nop 1
	v_cndmask_b32_e32 v95, v218, v95, vcc
